# GEMM main loops: issued-prefetch path gets its own copy of compute#1 + t1 LDS store with vmcnt+8 (no forced completion of just-issued t0 loads)
# baseline (speedup 1.0000x reference)
; #define MFMA(a, b, c) __builtin_amdgcn_mfma_f32_32x32x16_bf16((a), (b), (c), 0, 0, 0)
; DI void gt_compute(const bf16* asr, const bf16* bsr, f32x16& acc0, f32x16& acc1, f32x16& acc2, f32x16& acc3) {
;   bf16x8 a[4], b0[4], b1[4], b2[4], b3[4];
; #pragma unroll
;   for (int kk = 0; kk < 4; ++kk) {
;     a[kk] = *(const bf16x8*)(asr + kk * 16);
;     b0[kk] = *(const bf16x8*)(bsr + kk * 16);
;     b1[kk] = *(const bf16x8*)(bsr + 32 * LDT + kk * 16);
;     b2[kk] = *(const bf16x8*)(bsr + 64 * LDT + kk * 16);
;     b3[kk] = *(const bf16x8*)(bsr + 96 * LDT + kk * 16);
;   }
;   __builtin_amdgcn_sched_barrier(0);
;   __builtin_amdgcn_s_setprio(2);
; #pragma unroll
;   for (int kk = 0; kk < 4; ++kk) {
;     acc0 = MFMA(a[kk], b0[kk], acc0); acc1 = MFMA(a[kk], b1[kk], acc1); acc2 = MFMA(a[kk], b2[kk], acc2); acc3 = MFMA(a[kk], b3[kk], acc3);
;   }
;   __builtin_amdgcn_s_setprio(0);
;   __builtin_amdgcn_sched_barrier(0);
; }
; DI void gemm_mainloop(const bf16* __restrict__ A, int lda, const bf16* __restrict__ Bt, int ldb, int K, int m0, int n0,
;                       bf16* As, bf16* Bs, f32x16& acc0, f32x16& acc1, f32x16& acc2, f32x16& acc3) {
;     ...
;   for (int k0 = 0; k0 < K; k0 += 128) {
;     __syncthreads();
;     gt_store(t0, asw, bsw);
;     __syncthreads();
;     if (k0 + 128 < K) gt_load(t0, ap, bp, lda, ldb, KW(k0 + 128));
;     gt_compute(asr, bsr, acc0, acc1, acc2, acc3);
;     __syncthreads();
;     gt_store(t1, asw, bsw);
;     __syncthreads();
;     if (k0 + 192 < K) gt_load(t1, ap, bp, lda, ldb, KW(k0 + 192));
;     gt_compute(asr, bsr, acc0, acc1, acc2, acc3);
.LBB0_229:
	s_add_u32 s28, s20, 0x80
	s_addc_u32 s29, s21, 0
	s_cmpk_gt_u32 s20, 0x37f
	s_barrier
	s_waitcnt vmcnt(13)
	ds_write_b128 v140, v[72:75]
	ds_write_b128 v140, v[64:67] offset:4608
	ds_write_b128 v140, v[68:71] offset:9216
	s_waitcnt vmcnt(11)
	ds_write_b128 v140, v[80:83] offset:13824
	ds_write_b128 v140, v[76:79] offset:18432
	s_waitcnt vmcnt(10)
	ds_write_b128 v140, v[84:87] offset:23040
	s_waitcnt vmcnt(9)
	ds_write_b128 v140, v[96:99] offset:27648
	s_waitcnt vmcnt(8)
	ds_write_b128 v140, v[100:103] offset:32256
	s_waitcnt lgkmcnt(0)
	s_barrier
	s_cbranch_scc1 .LBB0_231
	s_cmp_lt_i32 s28, s15
	s_cselect_b32 s1, 0, -1
	s_cselect_b32 s0, 0, 0xfffffc00
	s_add_u32 s30, s18, s20
	s_addc_u32 s31, s19, s21
	s_add_u32 s0, s30, s0
	s_addc_u32 s1, s31, s1
	s_lshl_b64 s[0:1], s[0:1], 1
	v_lshl_add_u64 v[72:73], v[136:137], 0, s[0:1]
	v_add_co_u32_e32 v64, vcc, s48, v72
	v_lshl_add_u64 v[96:97], v[138:139], 0, s[0:1]
	s_nop 0
	v_addc_co_u32_e32 v65, vcc, 0, v73, vcc
	v_add_co_u32_e32 v68, vcc, 0x20000, v72
	s_nop 1
	v_addc_co_u32_e32 v69, vcc, 0, v73, vcc
	v_add_co_u32_e32 v80, vcc, 0x30000, v72
	global_load_dwordx4 v[64:67], v[64:65], off offset:256
	s_nop 0
	global_load_dwordx4 v[68:71], v[68:69], off offset:256
	v_addc_co_u32_e32 v81, vcc, 0, v73, vcc
	v_add_co_u32_e32 v84, vcc, 0x10000, v96
	global_load_dwordx4 v[72:75], v[72:73], off offset:256
	s_nop 0
	global_load_dwordx4 v[76:79], v[96:97], off offset:256
	v_addc_co_u32_e32 v85, vcc, 0, v97, vcc
	v_add_co_u32_e32 v98, vcc, 0x20000, v96
	global_load_dwordx4 v[80:83], v[80:81], off offset:256
	s_nop 0
	global_load_dwordx4 v[84:87], v[84:85], off offset:256
	v_addc_co_u32_e32 v99, vcc, 0, v97, vcc
	v_add_co_u32_e32 v100, vcc, 0x30000, v96
	s_nop 1
	v_addc_co_u32_e32 v101, vcc, 0, v97, vcc
	global_load_dwordx4 v[96:99], v[98:99], off offset:256
	s_nop 0
	global_load_dwordx4 v[100:103], v[100:101], off offset:256
	ds_read_b128 v[146:149], v142
	ds_read_b128 v[150:153], v142 offset:32
	ds_read_b128 v[154:157], v130 offset:18432
	ds_read_b128 v[162:165], v130 offset:18464
	ds_read_b128 v[166:169], v130 offset:23040
	ds_read_b128 v[170:173], v130 offset:23072
	ds_read_b128 v[174:177], v130 offset:27648
	ds_read_b128 v[178:181], v130 offset:27680
	ds_read_b128 v[182:185], v130 offset:32256
	ds_read_b128 v[186:189], v130 offset:32288
	ds_read_b128 v[190:193], v142 offset:64
	ds_read_b128 v[194:197], v142 offset:96
	ds_read_b128 v[198:201], v130 offset:18496
	ds_read_b128 v[202:205], v130 offset:18528
	ds_read_b128 v[206:209], v130 offset:23104
	ds_read_b128 v[210:213], v130 offset:23136
	ds_read_b128 v[214:217], v130 offset:27712
	ds_read_b128 v[218:221], v130 offset:27744
	ds_read_b128 v[222:225], v130 offset:32320
	ds_read_b128 v[226:229], v130 offset:32352
	s_setprio 2
	s_waitcnt lgkmcnt(14)
	v_mfma_f32_32x32x16_bf16 v[48:63], v[146:149], v[154:157], v[48:63]
	v_mfma_f32_32x32x16_bf16 v[32:47], v[146:149], v[166:169], v[32:47]
	s_waitcnt lgkmcnt(13)
	v_mfma_f32_32x32x16_bf16 v[16:31], v[146:149], v[174:177], v[16:31]
	s_waitcnt lgkmcnt(11)
	v_mfma_f32_32x32x16_bf16 v[0:15], v[146:149], v[182:185], v[0:15]
	v_mfma_f32_32x32x16_bf16 v[48:63], v[150:153], v[162:165], v[48:63]
	v_mfma_f32_32x32x16_bf16 v[32:47], v[150:153], v[170:173], v[32:47]
	v_mfma_f32_32x32x16_bf16 v[16:31], v[150:153], v[178:181], v[16:31]
	s_waitcnt lgkmcnt(10)
	v_mfma_f32_32x32x16_bf16 v[0:15], v[150:153], v[186:189], v[0:15]
	s_waitcnt lgkmcnt(7)
	v_mfma_f32_32x32x16_bf16 v[48:63], v[190:193], v[198:201], v[48:63]
	s_waitcnt lgkmcnt(5)
	v_mfma_f32_32x32x16_bf16 v[32:47], v[190:193], v[206:209], v[32:47]
	s_waitcnt lgkmcnt(3)
	v_mfma_f32_32x32x16_bf16 v[16:31], v[190:193], v[214:217], v[16:31]
	s_waitcnt lgkmcnt(1)
	v_mfma_f32_32x32x16_bf16 v[0:15], v[190:193], v[222:225], v[0:15]
	v_mfma_f32_32x32x16_bf16 v[48:63], v[194:197], v[202:205], v[48:63]
	v_mfma_f32_32x32x16_bf16 v[32:47], v[194:197], v[210:213], v[32:47]
	v_mfma_f32_32x32x16_bf16 v[16:31], v[194:197], v[218:221], v[16:31]
	s_waitcnt lgkmcnt(0)
	v_mfma_f32_32x32x16_bf16 v[0:15], v[194:197], v[226:229], v[0:15]
	s_setprio 0
	s_cmpk_gt_u32 s20, 0x33f
	s_barrier
	s_waitcnt vmcnt(13)
	ds_write_b128 v140, v[104:107]
	ds_write_b128 v140, v[88:91] offset:4608
	ds_write_b128 v140, v[92:95] offset:9216
	s_waitcnt vmcnt(11)
	ds_write_b128 v140, v[112:115] offset:13824
	ds_write_b128 v140, v[108:111] offset:18432
	s_waitcnt vmcnt(10)
	ds_write_b128 v140, v[116:119] offset:23040
	s_waitcnt vmcnt(9)
	ds_write_b128 v140, v[120:123] offset:27648
	s_waitcnt vmcnt(8)
	ds_write_b128 v140, v[124:127] offset:32256
	s_waitcnt lgkmcnt(0)
	s_barrier
	s_cbranch_scc1 .LBB0_228
	s_branch .Lmy_gw_0

; DI void gemm_mainloop(const bf16* __restrict__ A, int lda, const bf16* __restrict__ Bt, int ldb, int K, int m0, int n0,
;                       bf16* As, bf16* Bs, f32x16& acc0, f32x16& acc1, f32x16& acc2, f32x16& acc3) {
;     ...
;     if (k0 + 128 < K) gt_load(t0, ap, bp, lda, ldb, KW(k0 + 128));
;     gt_compute(asr, bsr, acc0, acc1, acc2, acc3);
;     __syncthreads();
;     gt_store(t1, asw, bsw);
;     __syncthreads();
;     if (k0 + 192 < K) gt_load(t1, ap, bp, lda, ldb, KW(k0 + 192));
.Lmy_gw_0:
	s_cmp_lt_i32 s20, s17
	s_cselect_b32 s1, 0, -1
	s_cselect_b32 s0, 0, 0xfffffc00
	s_add_u32 s20, s18, s20
	s_addc_u32 s21, s19, s21
	s_add_u32 s0, s20, s0
	s_addc_u32 s1, s21, s1
	s_lshl_b64 s[0:1], s[0:1], 1
	v_lshl_add_u64 v[104:105], v[136:137], 0, s[0:1]
	v_add_co_u32_e32 v106, vcc, s48, v104
	v_lshl_add_u64 v[120:121], v[138:139], 0, s[0:1]
	s_nop 0
	v_addc_co_u32_e32 v107, vcc, 0, v105, vcc
	v_add_co_u32_e32 v108, vcc, 0x20000, v104
	s_nop 1
	v_addc_co_u32_e32 v109, vcc, 0, v105, vcc
	v_add_co_u32_e32 v112, vcc, 0x30000, v104
	global_load_dwordx4 v[88:91], v[106:107], off offset:384
	global_load_dwordx4 v[92:95], v[108:109], off offset:384
	v_addc_co_u32_e32 v113, vcc, 0, v105, vcc
	v_add_co_u32_e32 v116, vcc, 0x10000, v120
	global_load_dwordx4 v[104:107], v[104:105], off offset:384
	s_nop 0
	global_load_dwordx4 v[108:111], v[120:121], off offset:384
	v_addc_co_u32_e32 v117, vcc, 0, v121, vcc
	v_add_co_u32_e32 v122, vcc, 0x20000, v120
	global_load_dwordx4 v[112:115], v[112:113], off offset:384
	s_nop 0
	global_load_dwordx4 v[116:119], v[116:117], off offset:384
	v_addc_co_u32_e32 v123, vcc, 0, v121, vcc
	v_add_co_u32_e32 v124, vcc, 0x30000, v120
	s_nop 1
	v_addc_co_u32_e32 v125, vcc, 0, v121, vcc
	global_load_dwordx4 v[120:123], v[122:123], off offset:384
	s_nop 0
	global_load_dwordx4 v[124:127], v[124:125], off offset:384
	s_branch .LBB0_228

; #define MFMA(a, b, c) __builtin_amdgcn_mfma_f32_32x32x16_bf16((a), (b), (c), 0, 0, 0)
; DI void gt_compute(const bf16* asr, const bf16* bsr, f32x16& acc0, f32x16& acc1, f32x16& acc2, f32x16& acc3) {
;   bf16x8 a[4], b0[4], b1[4], b2[4], b3[4];
; #pragma unroll
;   for (int kk = 0; kk < 4; ++kk) {
;     a[kk] = *(const bf16x8*)(asr + kk * 16);
;     b0[kk] = *(const bf16x8*)(bsr + kk * 16);
;     b1[kk] = *(const bf16x8*)(bsr + 32 * LDT + kk * 16);
;     b2[kk] = *(const bf16x8*)(bsr + 64 * LDT + kk * 16);
;     b3[kk] = *(const bf16x8*)(bsr + 96 * LDT + kk * 16);
;   }
;   __builtin_amdgcn_sched_barrier(0);
;   __builtin_amdgcn_s_setprio(2);
; #pragma unroll
;   for (int kk = 0; kk < 4; ++kk) {
;     acc0 = MFMA(a[kk], b0[kk], acc0); acc1 = MFMA(a[kk], b1[kk], acc1); acc2 = MFMA(a[kk], b2[kk], acc2); acc3 = MFMA(a[kk], b3[kk], acc3);
;   }
;   __builtin_amdgcn_s_setprio(0);
;   __builtin_amdgcn_sched_barrier(0);
; }
; DI void gemm_mainloop(const bf16* __restrict__ A, int lda, const bf16* __restrict__ Bt, int ldb, int K, int m0, int n0,
;                       bf16* As, bf16* Bs, f32x16& acc0, f32x16& acc1, f32x16& acc2, f32x16& acc3) {
;     ...
;   for (int k0 = 0; k0 < K; k0 += 128) {
;     __syncthreads();
;     gt_store(t0, asw, bsw);
;     __syncthreads();
;     if (k0 + 128 < K) gt_load(t0, ap, bp, lda, ldb, KW(k0 + 128));
;     gt_compute(asr, bsr, acc0, acc1, acc2, acc3);
;     __syncthreads();
;     gt_store(t1, asw, bsw);
;     __syncthreads();
;     if (k0 + 192 < K) gt_load(t1, ap, bp, lda, ldb, KW(k0 + 192));
;     gt_compute(asr, bsr, acc0, acc1, acc2, acc3);
.LBB0_481:
	s_add_u32 s34, s30, 0x80
	s_addc_u32 s35, s31, 0
	s_cmpk_gt_u32 s30, 0x37f
	s_waitcnt vmcnt(63) expcnt(7) lgkmcnt(15)
	s_barrier
	s_waitcnt vmcnt(13)
	ds_write_b128 v136, v[72:75]
	ds_write_b128 v136, v[64:67] offset:4608
	ds_write_b128 v136, v[68:71] offset:9216
	s_waitcnt vmcnt(11)
	ds_write_b128 v136, v[80:83] offset:13824
	ds_write_b128 v136, v[76:79] offset:18432
	s_waitcnt vmcnt(10)
	ds_write_b128 v136, v[84:87] offset:23040
	s_waitcnt vmcnt(9)
	ds_write_b128 v136, v[96:99] offset:27648
	s_waitcnt vmcnt(8)
	ds_write_b128 v136, v[104:107] offset:32256
	s_waitcnt lgkmcnt(0)
	s_barrier
	s_cbranch_scc1 .LBB0_483
	s_cmp_lt_i32 s34, s44
	s_cselect_b32 s7, 0, -1
	s_cselect_b32 s6, 0, 0xfffffc00
	s_add_u32 s46, s28, s30
	s_addc_u32 s47, s29, s31
	s_add_u32 s6, s46, s6
	s_addc_u32 s7, s47, s7
	s_lshl_b64 s[6:7], s[6:7], 1
	v_lshl_add_u64 v[72:73], v[132:133], 0, s[6:7]
	v_add_co_u32_e32 v64, vcc, s4, v72
	v_lshl_add_u64 v[96:97], v[134:135], 0, s[6:7]
	s_nop 0
	v_addc_co_u32_e32 v65, vcc, 0, v73, vcc
	v_add_co_u32_e32 v68, vcc, 0x20000, v72
	s_nop 1
	v_addc_co_u32_e32 v69, vcc, 0, v73, vcc
	v_add_co_u32_e32 v80, vcc, 0x30000, v72
	global_load_dwordx4 v[64:67], v[64:65], off offset:256
	s_nop 0
	global_load_dwordx4 v[68:71], v[68:69], off offset:256
	v_addc_co_u32_e32 v81, vcc, 0, v73, vcc
	v_add_co_u32_e32 v84, vcc, 0x10000, v96
	global_load_dwordx4 v[72:75], v[72:73], off offset:256
	s_nop 0
	global_load_dwordx4 v[76:79], v[96:97], off offset:256
	v_addc_co_u32_e32 v85, vcc, 0, v97, vcc
	v_add_co_u32_e32 v98, vcc, 0x20000, v96
	global_load_dwordx4 v[80:83], v[80:81], off offset:256
	s_nop 0
	global_load_dwordx4 v[84:87], v[84:85], off offset:256
	v_addc_co_u32_e32 v99, vcc, 0, v97, vcc
	v_add_co_u32_e32 v104, vcc, 0x30000, v96
	s_nop 1
	v_addc_co_u32_e32 v105, vcc, 0, v97, vcc
	global_load_dwordx4 v[96:99], v[98:99], off offset:256
	s_nop 0
	global_load_dwordx4 v[104:107], v[104:105], off offset:256
	ds_read_b128 v[142:145], v138
	ds_read_b128 v[146:149], v138 offset:32
	ds_read_b128 v[150:153], v128 offset:18432
	ds_read_b128 v[154:157], v128 offset:18464
	ds_read_b128 v[166:169], v128 offset:23040
	ds_read_b128 v[170:173], v128 offset:23072
	ds_read_b128 v[174:177], v128 offset:27648
	ds_read_b128 v[178:181], v128 offset:27680
	ds_read_b128 v[182:185], v128 offset:32256
	ds_read_b128 v[186:189], v128 offset:32288
	ds_read_b128 v[190:193], v138 offset:64
	ds_read_b128 v[194:197], v138 offset:96
	ds_read_b128 v[198:201], v128 offset:18496
	ds_read_b128 v[202:205], v128 offset:18528
	ds_read_b128 v[206:209], v128 offset:23104
	ds_read_b128 v[210:213], v128 offset:23136
	ds_read_b128 v[214:217], v128 offset:27712
	ds_read_b128 v[228:231], v128 offset:27744
	ds_read_b128 v[232:235], v128 offset:32320
	ds_read_b128 v[236:239], v128 offset:32352
	s_setprio 2
	s_waitcnt lgkmcnt(14)
	v_mfma_f32_32x32x16_bf16 v[48:63], v[142:145], v[150:153], v[48:63]
	v_mfma_f32_32x32x16_bf16 v[32:47], v[142:145], v[166:169], v[32:47]
	s_waitcnt lgkmcnt(13)
	v_mfma_f32_32x32x16_bf16 v[16:31], v[142:145], v[174:177], v[16:31]
	s_waitcnt lgkmcnt(11)
	v_mfma_f32_32x32x16_bf16 v[0:15], v[142:145], v[182:185], v[0:15]
	v_mfma_f32_32x32x16_bf16 v[48:63], v[146:149], v[154:157], v[48:63]
	v_mfma_f32_32x32x16_bf16 v[32:47], v[146:149], v[170:173], v[32:47]
	v_mfma_f32_32x32x16_bf16 v[16:31], v[146:149], v[178:181], v[16:31]
	s_waitcnt lgkmcnt(10)
	v_mfma_f32_32x32x16_bf16 v[0:15], v[146:149], v[186:189], v[0:15]
	s_waitcnt lgkmcnt(7)
	v_mfma_f32_32x32x16_bf16 v[48:63], v[190:193], v[198:201], v[48:63]
	s_waitcnt lgkmcnt(5)
	v_mfma_f32_32x32x16_bf16 v[32:47], v[190:193], v[206:209], v[32:47]
	s_waitcnt lgkmcnt(3)
	v_mfma_f32_32x32x16_bf16 v[16:31], v[190:193], v[214:217], v[16:31]
	s_waitcnt lgkmcnt(1)
	v_mfma_f32_32x32x16_bf16 v[0:15], v[190:193], v[232:235], v[0:15]
	v_mfma_f32_32x32x16_bf16 v[48:63], v[194:197], v[202:205], v[48:63]
	v_mfma_f32_32x32x16_bf16 v[32:47], v[194:197], v[210:213], v[32:47]
	v_mfma_f32_32x32x16_bf16 v[16:31], v[194:197], v[228:231], v[16:31]
	s_waitcnt lgkmcnt(0)
	v_mfma_f32_32x32x16_bf16 v[0:15], v[194:197], v[236:239], v[0:15]
	s_setprio 0
	s_cmpk_gt_u32 s30, 0x33f
	s_barrier
	s_waitcnt vmcnt(13)
	ds_write_b128 v136, v[100:103]
	ds_write_b128 v136, v[88:91] offset:4608
	ds_write_b128 v136, v[92:95] offset:9216
	s_waitcnt vmcnt(11)
	ds_write_b128 v136, v[112:115] offset:13824
	ds_write_b128 v136, v[108:111] offset:18432
	s_waitcnt vmcnt(10)
	ds_write_b128 v136, v[116:119] offset:23040
	s_waitcnt vmcnt(9)
	ds_write_b128 v136, v[120:123] offset:27648
	s_waitcnt vmcnt(8)
	ds_write_b128 v136, v[124:127] offset:32256
	s_waitcnt lgkmcnt(0)
	s_barrier
	s_cbranch_scc1 .LBB0_480
	s_branch .Lmy_gw_1

; DI void gemm_mainloop(const bf16* __restrict__ A, int lda, const bf16* __restrict__ Bt, int ldb, int K, int m0, int n0,
;                       bf16* As, bf16* Bs, f32x16& acc0, f32x16& acc1, f32x16& acc2, f32x16& acc3) {
;     ...
;     if (k0 + 128 < K) gt_load(t0, ap, bp, lda, ldb, KW(k0 + 128));
;     gt_compute(asr, bsr, acc0, acc1, acc2, acc3);
;     __syncthreads();
;     gt_store(t1, asw, bsw);
;     __syncthreads();
;     if (k0 + 192 < K) gt_load(t1, ap, bp, lda, ldb, KW(k0 + 192));
.Lmy_gw_1:
	s_cmp_lt_i32 s30, s45
	s_cselect_b32 s7, 0, -1
	s_cselect_b32 s6, 0, 0xfffffc00
	s_add_u32 s30, s28, s30
	s_addc_u32 s31, s29, s31
	s_add_u32 s6, s30, s6
	s_addc_u32 s7, s31, s7
	s_lshl_b64 s[6:7], s[6:7], 1
	v_lshl_add_u64 v[100:101], v[132:133], 0, s[6:7]
	v_add_co_u32_e32 v88, vcc, s4, v100
	v_lshl_add_u64 v[120:121], v[134:135], 0, s[6:7]
	s_nop 0
	v_addc_co_u32_e32 v89, vcc, 0, v101, vcc
	v_add_co_u32_e32 v92, vcc, 0x20000, v100
	s_nop 1
	v_addc_co_u32_e32 v93, vcc, 0, v101, vcc
	v_add_co_u32_e32 v112, vcc, 0x30000, v100
	global_load_dwordx4 v[88:91], v[88:89], off offset:384
	s_nop 0
	global_load_dwordx4 v[92:95], v[92:93], off offset:384
	v_addc_co_u32_e32 v113, vcc, 0, v101, vcc
	v_add_co_u32_e32 v116, vcc, 0x10000, v120
	global_load_dwordx4 v[100:103], v[100:101], off offset:384
	s_nop 0
	global_load_dwordx4 v[108:111], v[120:121], off offset:384
	v_addc_co_u32_e32 v117, vcc, 0, v121, vcc
	v_add_co_u32_e32 v122, vcc, 0x20000, v120
	global_load_dwordx4 v[112:115], v[112:113], off offset:384
	s_nop 0
	global_load_dwordx4 v[116:119], v[116:117], off offset:384
	v_addc_co_u32_e32 v123, vcc, 0, v121, vcc
	v_add_co_u32_e32 v124, vcc, 0x30000, v120
	s_nop 1
	v_addc_co_u32_e32 v125, vcc, 0, v121, vcc
	global_load_dwordx4 v[120:123], v[122:123], off offset:384
	s_nop 0
	global_load_dwordx4 v[124:127], v[124:125], off offset:384
	s_branch .LBB0_480

; #define MFMA(a, b, c) __builtin_amdgcn_mfma_f32_32x32x16_bf16((a), (b), (c), 0, 0, 0)
; DI void gt_compute(const bf16* asr, const bf16* bsr, f32x16& acc0, f32x16& acc1, f32x16& acc2, f32x16& acc3) {
;   bf16x8 a[4], b0[4], b1[4], b2[4], b3[4];
; #pragma unroll
;   for (int kk = 0; kk < 4; ++kk) {
;     a[kk] = *(const bf16x8*)(asr + kk * 16);
;     b0[kk] = *(const bf16x8*)(bsr + kk * 16);
;     b1[kk] = *(const bf16x8*)(bsr + 32 * LDT + kk * 16);
;     b2[kk] = *(const bf16x8*)(bsr + 64 * LDT + kk * 16);
;     b3[kk] = *(const bf16x8*)(bsr + 96 * LDT + kk * 16);
;   }
;   __builtin_amdgcn_sched_barrier(0);
;   __builtin_amdgcn_s_setprio(2);
; #pragma unroll
;   for (int kk = 0; kk < 4; ++kk) {
;     acc0 = MFMA(a[kk], b0[kk], acc0); acc1 = MFMA(a[kk], b1[kk], acc1); acc2 = MFMA(a[kk], b2[kk], acc2); acc3 = MFMA(a[kk], b3[kk], acc3);
;   }
;   __builtin_amdgcn_s_setprio(0);
;   __builtin_amdgcn_sched_barrier(0);
; }
; DI void gemm_mainloop(const bf16* __restrict__ A, int lda, const bf16* __restrict__ Bt, int ldb, int K, int m0, int n0,
;                       bf16* As, bf16* Bs, f32x16& acc0, f32x16& acc1, f32x16& acc2, f32x16& acc3) {
;     ...
;   for (int k0 = 0; k0 < K; k0 += 128) {
;     __syncthreads();
;     gt_store(t0, asw, bsw);
;     __syncthreads();
;     if (k0 + 128 < K) gt_load(t0, ap, bp, lda, ldb, KW(k0 + 128));
;     gt_compute(asr, bsr, acc0, acc1, acc2, acc3);
;     __syncthreads();
;     gt_store(t1, asw, bsw);
;     __syncthreads();
;     if (k0 + 192 < K) gt_load(t1, ap, bp, lda, ldb, KW(k0 + 192));
;     gt_compute(asr, bsr, acc0, acc1, acc2, acc3);
.LBB0_614:
	s_add_u32 s60, s58, 0x80
	s_addc_u32 s61, s59, 0
	s_cmpk_gt_u32 s58, 0x37f
	s_waitcnt vmcnt(63) expcnt(7) lgkmcnt(15)
	s_barrier
	s_waitcnt vmcnt(13)
	ds_write_b128 v142, v[72:75]
	ds_write_b128 v142, v[64:67] offset:4608
	ds_write_b128 v142, v[68:71] offset:9216
	s_waitcnt vmcnt(11)
	ds_write_b128 v142, v[80:83] offset:13824
	ds_write_b128 v142, v[76:79] offset:18432
	s_waitcnt vmcnt(10)
	ds_write_b128 v142, v[84:87] offset:23040
	s_waitcnt vmcnt(9)
	ds_write_b128 v142, v[96:99] offset:27648
	s_waitcnt vmcnt(8)
	ds_write_b128 v142, v[104:107] offset:32256
	s_waitcnt lgkmcnt(0)
	s_barrier
	s_cbranch_scc1 .LBB0_616
	s_cmp_lt_i32 s60, s86
	s_cselect_b32 s0, 0, -1
	s_cselect_b32 s1, 0, 0xfffffc00
	s_add_u32 s6, s28, s58
	s_addc_u32 s7, s29, s59
	s_add_u32 s6, s6, s1
	s_addc_u32 s7, s7, s0
	s_lshl_b64 s[6:7], s[6:7], 1
	v_lshl_add_u64 v[72:73], v[138:139], 0, s[6:7]
	v_add_co_u32_e32 v64, vcc, s68, v72
	v_lshl_add_u64 v[96:97], v[140:141], 0, s[6:7]
	s_nop 0
	v_addc_co_u32_e32 v65, vcc, 0, v73, vcc
	v_add_co_u32_e32 v68, vcc, 0x20000, v72
	s_nop 1
	v_addc_co_u32_e32 v69, vcc, 0, v73, vcc
	v_add_co_u32_e32 v80, vcc, 0x30000, v72
	global_load_dwordx4 v[64:67], v[64:65], off offset:256
	s_nop 0
	global_load_dwordx4 v[68:71], v[68:69], off offset:256
	v_addc_co_u32_e32 v81, vcc, 0, v73, vcc
	v_add_co_u32_e32 v84, vcc, 0x10000, v96
	global_load_dwordx4 v[72:75], v[72:73], off offset:256
	s_nop 0
	global_load_dwordx4 v[76:79], v[96:97], off offset:256
	v_addc_co_u32_e32 v85, vcc, 0, v97, vcc
	v_add_co_u32_e32 v98, vcc, 0x20000, v96
	global_load_dwordx4 v[80:83], v[80:81], off offset:256
	s_nop 0
	global_load_dwordx4 v[84:87], v[84:85], off offset:256
	v_addc_co_u32_e32 v99, vcc, 0, v97, vcc
	v_add_co_u32_e32 v104, vcc, 0x30000, v96
	s_nop 1
	v_addc_co_u32_e32 v105, vcc, 0, v97, vcc
	global_load_dwordx4 v[96:99], v[98:99], off offset:256
	s_nop 0
	global_load_dwordx4 v[104:107], v[104:105], off offset:256
	ds_read_b128 v[156:159], v144
	ds_read_b128 v[162:165], v144 offset:32
	ds_read_b128 v[166:169], v128 offset:18432
	ds_read_b128 v[170:173], v128 offset:18464
	ds_read_b128 v[174:177], v128 offset:23040
	ds_read_b128 v[178:181], v128 offset:23072
	ds_read_b128 v[182:185], v128 offset:27648
	ds_read_b128 v[186:189], v128 offset:27680
	ds_read_b128 v[190:193], v128 offset:32256
	ds_read_b128 v[194:197], v128 offset:32288
	ds_read_b128 v[198:201], v144 offset:64
	ds_read_b128 v[202:205], v144 offset:96
	ds_read_b128 v[206:209], v128 offset:18496
	ds_read_b128 v[210:213], v128 offset:18528
	ds_read_b128 v[214:217], v128 offset:23104
	ds_read_b128 v[228:231], v128 offset:23136
	ds_read_b128 v[232:235], v128 offset:27712
	ds_read_b128 v[236:239], v128 offset:27744
	ds_read_b128 v[240:243], v128 offset:32320
	ds_read_b128 v[244:247], v128 offset:32352
	s_setprio 2
	s_waitcnt lgkmcnt(14)
	v_mfma_f32_32x32x16_bf16 v[32:47], v[156:159], v[166:169], v[32:47]
	v_mfma_f32_32x32x16_bf16 v[48:63], v[156:159], v[174:177], v[48:63]
	s_waitcnt lgkmcnt(13)
	v_mfma_f32_32x32x16_bf16 v[16:31], v[156:159], v[182:185], v[16:31]
	s_waitcnt lgkmcnt(11)
	v_mfma_f32_32x32x16_bf16 v[0:15], v[156:159], v[190:193], v[0:15]
	v_mfma_f32_32x32x16_bf16 v[32:47], v[162:165], v[170:173], v[32:47]
	v_mfma_f32_32x32x16_bf16 v[48:63], v[162:165], v[178:181], v[48:63]
	v_mfma_f32_32x32x16_bf16 v[16:31], v[162:165], v[186:189], v[16:31]
	s_waitcnt lgkmcnt(10)
	v_mfma_f32_32x32x16_bf16 v[0:15], v[162:165], v[194:197], v[0:15]
	s_waitcnt lgkmcnt(7)
	v_mfma_f32_32x32x16_bf16 v[32:47], v[198:201], v[206:209], v[32:47]
	s_waitcnt lgkmcnt(5)
	v_mfma_f32_32x32x16_bf16 v[48:63], v[198:201], v[214:217], v[48:63]
	s_waitcnt lgkmcnt(3)
	v_mfma_f32_32x32x16_bf16 v[16:31], v[198:201], v[232:235], v[16:31]
	s_waitcnt lgkmcnt(1)
	v_mfma_f32_32x32x16_bf16 v[0:15], v[198:201], v[240:243], v[0:15]
	v_mfma_f32_32x32x16_bf16 v[32:47], v[202:205], v[210:213], v[32:47]
	v_mfma_f32_32x32x16_bf16 v[48:63], v[202:205], v[228:231], v[48:63]
	v_mfma_f32_32x32x16_bf16 v[16:31], v[202:205], v[236:239], v[16:31]
	s_waitcnt lgkmcnt(0)
	v_mfma_f32_32x32x16_bf16 v[0:15], v[202:205], v[244:247], v[0:15]
	s_setprio 0
	s_cmpk_gt_u32 s58, 0x33f
	s_barrier
	s_waitcnt vmcnt(13)
	ds_write_b128 v142, v[100:103]
	ds_write_b128 v142, v[88:91] offset:4608
	ds_write_b128 v142, v[92:95] offset:9216
	s_waitcnt vmcnt(11)
	ds_write_b128 v142, v[112:115] offset:13824
	ds_write_b128 v142, v[108:111] offset:18432
	s_waitcnt vmcnt(10)
	ds_write_b128 v142, v[116:119] offset:23040
	s_waitcnt vmcnt(9)
	ds_write_b128 v142, v[120:123] offset:27648
	s_waitcnt vmcnt(8)
	ds_write_b128 v142, v[124:127] offset:32256
	s_waitcnt lgkmcnt(0)
	s_barrier
	s_cbranch_scc1 .LBB0_613
	s_branch .Lmy_gw_2

; DI void gemm_mainloop(const bf16* __restrict__ A, int lda, const bf16* __restrict__ Bt, int ldb, int K, int m0, int n0,
;                       bf16* As, bf16* Bs, f32x16& acc0, f32x16& acc1, f32x16& acc2, f32x16& acc3) {
;     ...
;     if (k0 + 128 < K) gt_load(t0, ap, bp, lda, ldb, KW(k0 + 128));
;     gt_compute(asr, bsr, acc0, acc1, acc2, acc3);
;     __syncthreads();
;     gt_store(t1, asw, bsw);
;     __syncthreads();
;     if (k0 + 192 < K) gt_load(t1, ap, bp, lda, ldb, KW(k0 + 192));
.Lmy_gw_2:
	s_cmp_lt_i32 s58, s87
	s_cselect_b32 s0, 0, -1
	s_cselect_b32 s1, 0, 0xfffffc00
	s_add_u32 s6, s28, s58
	s_addc_u32 s7, s29, s59
	s_add_u32 s6, s6, s1
	s_addc_u32 s7, s7, s0
	s_lshl_b64 s[6:7], s[6:7], 1
	v_lshl_add_u64 v[100:101], v[138:139], 0, s[6:7]
	v_add_co_u32_e32 v88, vcc, s68, v100
	v_lshl_add_u64 v[120:121], v[140:141], 0, s[6:7]
	s_nop 0
	v_addc_co_u32_e32 v89, vcc, 0, v101, vcc
	v_add_co_u32_e32 v92, vcc, 0x20000, v100
	s_nop 1
	v_addc_co_u32_e32 v93, vcc, 0, v101, vcc
	v_add_co_u32_e32 v112, vcc, 0x30000, v100
	global_load_dwordx4 v[88:91], v[88:89], off offset:384
	s_nop 0
	global_load_dwordx4 v[92:95], v[92:93], off offset:384
	v_addc_co_u32_e32 v113, vcc, 0, v101, vcc
	v_add_co_u32_e32 v116, vcc, 0x10000, v120
	global_load_dwordx4 v[100:103], v[100:101], off offset:384
	s_nop 0
	global_load_dwordx4 v[108:111], v[120:121], off offset:384
	v_addc_co_u32_e32 v117, vcc, 0, v121, vcc
	v_add_co_u32_e32 v122, vcc, 0x20000, v120
	global_load_dwordx4 v[112:115], v[112:113], off offset:384
	s_nop 0
	global_load_dwordx4 v[116:119], v[116:117], off offset:384
	v_addc_co_u32_e32 v123, vcc, 0, v121, vcc
	v_add_co_u32_e32 v124, vcc, 0x30000, v120
	s_nop 1
	v_addc_co_u32_e32 v125, vcc, 0, v121, vcc
	global_load_dwordx4 v[120:123], v[122:123], off offset:384
	s_nop 0
	global_load_dwordx4 v[124:127], v[124:125], off offset:384
	s_branch .LBB0_613

; #define MFMA(a, b, c) __builtin_amdgcn_mfma_f32_32x32x16_bf16((a), (b), (c), 0, 0, 0)
; DI void gt_compute(const bf16* asr, const bf16* bsr, f32x16& acc0, f32x16& acc1, f32x16& acc2, f32x16& acc3) {
;   bf16x8 a[4], b0[4], b1[4], b2[4], b3[4];
; #pragma unroll
;   for (int kk = 0; kk < 4; ++kk) {
;     a[kk] = *(const bf16x8*)(asr + kk * 16);
;     b0[kk] = *(const bf16x8*)(bsr + kk * 16);
;     b1[kk] = *(const bf16x8*)(bsr + 32 * LDT + kk * 16);
;     b2[kk] = *(const bf16x8*)(bsr + 64 * LDT + kk * 16);
;     b3[kk] = *(const bf16x8*)(bsr + 96 * LDT + kk * 16);
;   }
;   __builtin_amdgcn_sched_barrier(0);
;   __builtin_amdgcn_s_setprio(2);
; #pragma unroll
;   for (int kk = 0; kk < 4; ++kk) {
;     acc0 = MFMA(a[kk], b0[kk], acc0); acc1 = MFMA(a[kk], b1[kk], acc1); acc2 = MFMA(a[kk], b2[kk], acc2); acc3 = MFMA(a[kk], b3[kk], acc3);
;   }
;   __builtin_amdgcn_s_setprio(0);
;   __builtin_amdgcn_sched_barrier(0);
; }
; DI void gemm_mainloop(const bf16* __restrict__ A, int lda, const bf16* __restrict__ Bt, int ldb, int K, int m0, int n0,
;                       bf16* As, bf16* Bs, f32x16& acc0, f32x16& acc1, f32x16& acc2, f32x16& acc3) {
;     ...
;   for (int k0 = 0; k0 < K; k0 += 128) {
;     __syncthreads();
;     gt_store(t0, asw, bsw);
;     __syncthreads();
;     if (k0 + 128 < K) gt_load(t0, ap, bp, lda, ldb, KW(k0 + 128));
;     gt_compute(asr, bsr, acc0, acc1, acc2, acc3);
;     __syncthreads();
;     gt_store(t1, asw, bsw);
;     __syncthreads();
;     if (k0 + 192 < K) gt_load(t1, ap, bp, lda, ldb, KW(k0 + 192));
;     gt_compute(asr, bsr, acc0, acc1, acc2, acc3);
.LBB0_951:
	s_add_u32 s50, s48, 0x80
	s_addc_u32 s51, s49, 0
	s_cmpk_gt_u32 s48, 0x37f
	s_waitcnt vmcnt(63) expcnt(7) lgkmcnt(15)
	s_barrier
	s_waitcnt vmcnt(13)
	ds_write_b128 v150, v[72:75]
	ds_write_b128 v150, v[64:67] offset:4608
	ds_write_b128 v150, v[68:71] offset:9216
	s_waitcnt vmcnt(11)
	ds_write_b128 v150, v[80:83] offset:13824
	ds_write_b128 v150, v[76:79] offset:18432
	s_waitcnt vmcnt(10)
	ds_write_b128 v150, v[84:87] offset:23040
	s_waitcnt vmcnt(9)
	ds_write_b128 v150, v[96:99] offset:27648
	s_waitcnt vmcnt(8)
	ds_write_b128 v150, v[104:107] offset:32256
	s_waitcnt lgkmcnt(0)
	s_barrier
	s_cbranch_scc1 .LBB0_953
	s_cmp_lt_i32 s50, s30
	s_cselect_b32 s7, 0, -1
	s_cselect_b32 s6, 0, 0xfffffc00
	s_add_u32 s65, s28, s48
	s_addc_u32 s66, s29, s49
	s_add_u32 s6, s65, s6
	s_addc_u32 s7, s66, s7
	s_lshl_b64 s[6:7], s[6:7], 1
	v_lshl_add_u64 v[72:73], v[146:147], 0, s[6:7]
	v_add_co_u32_e32 v64, vcc, s59, v72
	v_lshl_add_u64 v[96:97], v[148:149], 0, s[6:7]
	s_nop 0
	v_addc_co_u32_e32 v65, vcc, 0, v73, vcc
	v_add_co_u32_e32 v68, vcc, 0x20000, v72
	s_nop 1
	v_addc_co_u32_e32 v69, vcc, 0, v73, vcc
	v_add_co_u32_e32 v80, vcc, 0x30000, v72
	global_load_dwordx4 v[64:67], v[64:65], off offset:256
	s_nop 0
	global_load_dwordx4 v[68:71], v[68:69], off offset:256
	v_addc_co_u32_e32 v81, vcc, 0, v73, vcc
	v_add_co_u32_e32 v84, vcc, 0x10000, v96
	global_load_dwordx4 v[72:75], v[72:73], off offset:256
	s_nop 0
	global_load_dwordx4 v[76:79], v[96:97], off offset:256
	v_addc_co_u32_e32 v85, vcc, 0, v97, vcc
	v_add_co_u32_e32 v98, vcc, 0x20000, v96
	global_load_dwordx4 v[80:83], v[80:81], off offset:256
	s_nop 0
	global_load_dwordx4 v[84:87], v[84:85], off offset:256
	v_addc_co_u32_e32 v99, vcc, 0, v97, vcc
	v_add_co_u32_e32 v104, vcc, 0x30000, v96
	s_nop 1
	v_addc_co_u32_e32 v105, vcc, 0, v97, vcc
	global_load_dwordx4 v[96:99], v[98:99], off offset:256
	s_nop 0
	global_load_dwordx4 v[104:107], v[104:105], off offset:256
	ds_read_b128 v[174:177], v152
	ds_read_b128 v[178:181], v152 offset:32
	ds_read_b128 v[182:185], v130 offset:18432
	ds_read_b128 v[186:189], v130 offset:18464
	ds_read_b128 v[190:193], v130 offset:23040
	ds_read_b128 v[194:197], v130 offset:23072
	ds_read_b128 v[198:201], v130 offset:27648
	ds_read_b128 v[202:205], v130 offset:27680
	ds_read_b128 v[206:209], v130 offset:32256
	ds_read_b128 v[210:213], v130 offset:32288
	ds_read_b128 v[214:217], v152 offset:64
	ds_read_b128 v[226:229], v152 offset:96
	ds_read_b128 v[230:233], v130 offset:18496
	ds_read_b128 v[234:237], v130 offset:18528
	ds_read_b128 v[238:241], v130 offset:23104
	ds_read_b128 v[242:245], v130 offset:23136
	ds_read_b128 v[246:249], v130 offset:27712
	ds_read_b128 v[250:253], v130 offset:27744
	ds_read_b128 v[156:159], v130 offset:32320
	ds_read_b128 v[162:165], v130 offset:32352
	s_setprio 2
	s_waitcnt lgkmcnt(14)
	v_mfma_f32_32x32x16_bf16 v[48:63], v[174:177], v[182:185], v[48:63]
	v_mfma_f32_32x32x16_bf16 v[16:31], v[174:177], v[190:193], v[16:31]
	s_waitcnt lgkmcnt(13)
	v_mfma_f32_32x32x16_bf16 v[32:47], v[174:177], v[198:201], v[32:47]
	s_waitcnt lgkmcnt(11)
	v_mfma_f32_32x32x16_bf16 v[0:15], v[174:177], v[206:209], v[0:15]
	v_mfma_f32_32x32x16_bf16 v[48:63], v[178:181], v[186:189], v[48:63]
	v_mfma_f32_32x32x16_bf16 v[16:31], v[178:181], v[194:197], v[16:31]
	v_mfma_f32_32x32x16_bf16 v[32:47], v[178:181], v[202:205], v[32:47]
	s_waitcnt lgkmcnt(10)
	v_mfma_f32_32x32x16_bf16 v[0:15], v[178:181], v[210:213], v[0:15]
	s_waitcnt lgkmcnt(7)
	v_mfma_f32_32x32x16_bf16 v[48:63], v[214:217], v[230:233], v[48:63]
	s_waitcnt lgkmcnt(5)
	v_mfma_f32_32x32x16_bf16 v[16:31], v[214:217], v[238:241], v[16:31]
	s_waitcnt lgkmcnt(3)
	v_mfma_f32_32x32x16_bf16 v[32:47], v[214:217], v[246:249], v[32:47]
	s_waitcnt lgkmcnt(1)
	v_mfma_f32_32x32x16_bf16 v[0:15], v[214:217], v[156:159], v[0:15]
	v_mfma_f32_32x32x16_bf16 v[48:63], v[226:229], v[234:237], v[48:63]
	v_mfma_f32_32x32x16_bf16 v[16:31], v[226:229], v[242:245], v[16:31]
	v_mfma_f32_32x32x16_bf16 v[32:47], v[226:229], v[250:253], v[32:47]
	s_waitcnt lgkmcnt(0)
	v_mfma_f32_32x32x16_bf16 v[0:15], v[226:229], v[162:165], v[0:15]
	s_setprio 0
	s_cmpk_gt_u32 s48, 0x33f
	s_barrier
	s_waitcnt vmcnt(13)
	ds_write_b128 v150, v[100:103]
	ds_write_b128 v150, v[88:91] offset:4608
	ds_write_b128 v150, v[92:95] offset:9216
	s_waitcnt vmcnt(11)
	ds_write_b128 v150, v[112:115] offset:13824
	ds_write_b128 v150, v[108:111] offset:18432
	s_waitcnt vmcnt(10)
	ds_write_b128 v150, v[116:119] offset:23040
	s_waitcnt vmcnt(9)
	ds_write_b128 v150, v[120:123] offset:27648
	s_waitcnt vmcnt(8)
	ds_write_b128 v150, v[124:127] offset:32256
	s_waitcnt lgkmcnt(0)
	s_barrier
	s_cbranch_scc1 .LBB0_950
	s_branch .Lmy_gw_3

; DI void gemm_mainloop(const bf16* __restrict__ A, int lda, const bf16* __restrict__ Bt, int ldb, int K, int m0, int n0,
;                       bf16* As, bf16* Bs, f32x16& acc0, f32x16& acc1, f32x16& acc2, f32x16& acc3) {
;     ...
;     if (k0 + 128 < K) gt_load(t0, ap, bp, lda, ldb, KW(k0 + 128));
;     gt_compute(asr, bsr, acc0, acc1, acc2, acc3);
;     __syncthreads();
;     gt_store(t1, asw, bsw);
;     __syncthreads();
;     if (k0 + 192 < K) gt_load(t1, ap, bp, lda, ldb, KW(k0 + 192));
.Lmy_gw_3:
	s_cmp_lt_i32 s48, s31
	s_cselect_b32 s7, 0, -1
	s_cselect_b32 s6, 0, 0xfffffc00
	s_add_u32 s48, s28, s48
	s_addc_u32 s49, s29, s49
	s_add_u32 s6, s48, s6
	s_addc_u32 s7, s49, s7
	s_lshl_b64 s[6:7], s[6:7], 1
	v_lshl_add_u64 v[100:101], v[146:147], 0, s[6:7]
	v_add_co_u32_e32 v88, vcc, s59, v100
	v_lshl_add_u64 v[120:121], v[148:149], 0, s[6:7]
	s_nop 0
	v_addc_co_u32_e32 v89, vcc, 0, v101, vcc
	v_add_co_u32_e32 v92, vcc, 0x20000, v100
	s_nop 1
	v_addc_co_u32_e32 v93, vcc, 0, v101, vcc
	v_add_co_u32_e32 v112, vcc, 0x30000, v100
	global_load_dwordx4 v[88:91], v[88:89], off offset:384
	s_nop 0
	global_load_dwordx4 v[92:95], v[92:93], off offset:384
	v_addc_co_u32_e32 v113, vcc, 0, v101, vcc
	v_add_co_u32_e32 v116, vcc, 0x10000, v120
	global_load_dwordx4 v[100:103], v[100:101], off offset:384
	s_nop 0
	global_load_dwordx4 v[108:111], v[120:121], off offset:384
	v_addc_co_u32_e32 v117, vcc, 0, v121, vcc
	v_add_co_u32_e32 v122, vcc, 0x20000, v120
	global_load_dwordx4 v[112:115], v[112:113], off offset:384
	s_nop 0
	global_load_dwordx4 v[116:119], v[116:117], off offset:384
	v_addc_co_u32_e32 v123, vcc, 0, v121, vcc
	v_add_co_u32_e32 v124, vcc, 0x30000, v120
	s_nop 1
	v_addc_co_u32_e32 v125, vcc, 0, v121, vcc
	global_load_dwordx4 v[120:123], v[122:123], off offset:384
	s_nop 0
	global_load_dwordx4 v[124:127], v[124:125], off offset:384
	s_branch .LBB0_950

; #define MFMA(a, b, c) __builtin_amdgcn_mfma_f32_32x32x16_bf16((a), (b), (c), 0, 0, 0)
; DI void gt_compute(const bf16* asr, const bf16* bsr, f32x16& acc0, f32x16& acc1, f32x16& acc2, f32x16& acc3) {
;   bf16x8 a[4], b0[4], b1[4], b2[4], b3[4];
; #pragma unroll
;   for (int kk = 0; kk < 4; ++kk) {
;     a[kk] = *(const bf16x8*)(asr + kk * 16);
;     b0[kk] = *(const bf16x8*)(bsr + kk * 16);
;     b1[kk] = *(const bf16x8*)(bsr + 32 * LDT + kk * 16);
;     b2[kk] = *(const bf16x8*)(bsr + 64 * LDT + kk * 16);
;     b3[kk] = *(const bf16x8*)(bsr + 96 * LDT + kk * 16);
;   }
;   __builtin_amdgcn_sched_barrier(0);
;   __builtin_amdgcn_s_setprio(2);
; #pragma unroll
;   for (int kk = 0; kk < 4; ++kk) {
;     acc0 = MFMA(a[kk], b0[kk], acc0); acc1 = MFMA(a[kk], b1[kk], acc1); acc2 = MFMA(a[kk], b2[kk], acc2); acc3 = MFMA(a[kk], b3[kk], acc3);
;   }
;   __builtin_amdgcn_s_setprio(0);
;   __builtin_amdgcn_sched_barrier(0);
; }
; DI void gemm_mainloop(const bf16* __restrict__ A, int lda, const bf16* __restrict__ Bt, int ldb, int K, int m0, int n0,
;                       bf16* As, bf16* Bs, f32x16& acc0, f32x16& acc1, f32x16& acc2, f32x16& acc3) {
;     ...
;   for (int k0 = 0; k0 < K; k0 += 128) {
;     __syncthreads();
;     gt_store(t0, asw, bsw);
;     __syncthreads();
;     if (k0 + 128 < K) gt_load(t0, ap, bp, lda, ldb, KW(k0 + 128));
;     gt_compute(asr, bsr, acc0, acc1, acc2, acc3);
;     __syncthreads();
;     gt_store(t1, asw, bsw);
;     __syncthreads();
;     if (k0 + 192 < K) gt_load(t1, ap, bp, lda, ldb, KW(k0 + 192));
;     gt_compute(asr, bsr, acc0, acc1, acc2, acc3);
.LBB0_1319:
	s_add_u32 s16, s14, 0x80
	s_addc_u32 s17, s15, 0
	s_cmpk_gt_u32 s14, 0x37f
	s_waitcnt vmcnt(63) expcnt(7) lgkmcnt(15)
	s_barrier
	s_waitcnt vmcnt(13)
	ds_write_b128 v136, v[72:75]
	ds_write_b128 v136, v[64:67] offset:4608
	ds_write_b128 v136, v[68:71] offset:9216
	s_waitcnt vmcnt(11)
	ds_write_b128 v136, v[80:83] offset:13824
	ds_write_b128 v136, v[76:79] offset:18432
	s_waitcnt vmcnt(10)
	ds_write_b128 v136, v[84:87] offset:23040
	s_waitcnt vmcnt(9)
	ds_write_b128 v136, v[96:99] offset:27648
	s_waitcnt vmcnt(8)
	ds_write_b128 v136, v[100:103] offset:32256
	s_waitcnt lgkmcnt(0)
	s_barrier
	s_cbranch_scc1 .LBB0_1321
	s_cmp_lt_i32 s16, s25
	s_cselect_b32 s0, 0, -1
	s_cselect_b32 s1, 0, 0xfffffc00
	s_add_u32 s6, s12, s14
	s_addc_u32 s7, s13, s15
	s_add_u32 s6, s6, s1
	s_addc_u32 s7, s7, s0
	s_lshl_b64 s[6:7], s[6:7], 1
	v_lshl_add_u64 v[72:73], v[132:133], 0, s[6:7]
	v_add_co_u32_e32 v64, vcc, s4, v72
	v_lshl_add_u64 v[96:97], v[134:135], 0, s[6:7]
	s_nop 0
	v_addc_co_u32_e32 v65, vcc, 0, v73, vcc
	v_add_co_u32_e32 v68, vcc, 0x20000, v72
	s_nop 1
	v_addc_co_u32_e32 v69, vcc, 0, v73, vcc
	v_add_co_u32_e32 v80, vcc, 0x30000, v72
	global_load_dwordx4 v[64:67], v[64:65], off offset:256
	s_nop 0
	global_load_dwordx4 v[68:71], v[68:69], off offset:256
	v_addc_co_u32_e32 v81, vcc, 0, v73, vcc
	v_add_co_u32_e32 v84, vcc, 0x10000, v96
	global_load_dwordx4 v[72:75], v[72:73], off offset:256
	s_nop 0
	global_load_dwordx4 v[76:79], v[96:97], off offset:256
	v_addc_co_u32_e32 v85, vcc, 0, v97, vcc
	v_add_co_u32_e32 v98, vcc, 0x20000, v96
	global_load_dwordx4 v[80:83], v[80:81], off offset:256
	s_nop 0
	global_load_dwordx4 v[84:87], v[84:85], off offset:256
	v_addc_co_u32_e32 v99, vcc, 0, v97, vcc
	v_add_co_u32_e32 v100, vcc, 0x30000, v96
	s_nop 1
	v_addc_co_u32_e32 v101, vcc, 0, v97, vcc
	global_load_dwordx4 v[96:99], v[98:99], off offset:256
	s_nop 0
	global_load_dwordx4 v[100:103], v[100:101], off offset:256
	ds_read_b128 v[142:145], v138
	ds_read_b128 v[146:149], v138 offset:32
	ds_read_b128 v[150:153], v128 offset:18432
	ds_read_b128 v[154:157], v128 offset:18464
	ds_read_b128 v[162:165], v128 offset:23040
	ds_read_b128 v[166:169], v128 offset:23072
	ds_read_b128 v[170:173], v128 offset:27648
	ds_read_b128 v[174:177], v128 offset:27680
	ds_read_b128 v[178:181], v128 offset:32256
	ds_read_b128 v[182:185], v128 offset:32288
	ds_read_b128 v[186:189], v138 offset:64
	ds_read_b128 v[190:193], v138 offset:96
	ds_read_b128 v[194:197], v128 offset:18496
	ds_read_b128 v[198:201], v128 offset:18528
	ds_read_b128 v[202:205], v128 offset:23104
	ds_read_b128 v[206:209], v128 offset:23136
	ds_read_b128 v[210:213], v128 offset:27712
	ds_read_b128 v[214:217], v128 offset:27744
	ds_read_b128 v[226:229], v128 offset:32320
	ds_read_b128 v[230:233], v128 offset:32352
	s_setprio 2
	s_waitcnt lgkmcnt(14)
	v_mfma_f32_32x32x16_bf16 v[48:63], v[142:145], v[150:153], v[48:63]
	v_mfma_f32_32x32x16_bf16 v[32:47], v[142:145], v[162:165], v[32:47]
	s_waitcnt lgkmcnt(13)
	v_mfma_f32_32x32x16_bf16 v[16:31], v[142:145], v[170:173], v[16:31]
	s_waitcnt lgkmcnt(11)
	v_mfma_f32_32x32x16_bf16 v[0:15], v[142:145], v[178:181], v[0:15]
	v_mfma_f32_32x32x16_bf16 v[48:63], v[146:149], v[154:157], v[48:63]
	v_mfma_f32_32x32x16_bf16 v[32:47], v[146:149], v[166:169], v[32:47]
	v_mfma_f32_32x32x16_bf16 v[16:31], v[146:149], v[174:177], v[16:31]
	s_waitcnt lgkmcnt(10)
	v_mfma_f32_32x32x16_bf16 v[0:15], v[146:149], v[182:185], v[0:15]
	s_waitcnt lgkmcnt(7)
	v_mfma_f32_32x32x16_bf16 v[48:63], v[186:189], v[194:197], v[48:63]
	s_waitcnt lgkmcnt(5)
	v_mfma_f32_32x32x16_bf16 v[32:47], v[186:189], v[202:205], v[32:47]
	s_waitcnt lgkmcnt(3)
	v_mfma_f32_32x32x16_bf16 v[16:31], v[186:189], v[210:213], v[16:31]
	s_waitcnt lgkmcnt(1)
	v_mfma_f32_32x32x16_bf16 v[0:15], v[186:189], v[226:229], v[0:15]
	v_mfma_f32_32x32x16_bf16 v[48:63], v[190:193], v[198:201], v[48:63]
	v_mfma_f32_32x32x16_bf16 v[32:47], v[190:193], v[206:209], v[32:47]
	v_mfma_f32_32x32x16_bf16 v[16:31], v[190:193], v[214:217], v[16:31]
	s_waitcnt lgkmcnt(0)
	v_mfma_f32_32x32x16_bf16 v[0:15], v[190:193], v[230:233], v[0:15]
	s_setprio 0
	s_cmpk_gt_u32 s14, 0x33f
	s_barrier
	s_waitcnt vmcnt(13)
	ds_write_b128 v136, v[104:107]
	ds_write_b128 v136, v[88:91] offset:4608
	ds_write_b128 v136, v[92:95] offset:9216
	s_waitcnt vmcnt(11)
	ds_write_b128 v136, v[112:115] offset:13824
	ds_write_b128 v136, v[108:111] offset:18432
	s_waitcnt vmcnt(10)
	ds_write_b128 v136, v[116:119] offset:23040
	s_waitcnt vmcnt(9)
	ds_write_b128 v136, v[120:123] offset:27648
	s_waitcnt vmcnt(8)
	ds_write_b128 v136, v[124:127] offset:32256
	s_waitcnt lgkmcnt(0)
	s_barrier
	s_cbranch_scc1 .LBB0_1318
	s_branch .Lmy_gw_4

; DI void gemm_mainloop(const bf16* __restrict__ A, int lda, const bf16* __restrict__ Bt, int ldb, int K, int m0, int n0,
;                       bf16* As, bf16* Bs, f32x16& acc0, f32x16& acc1, f32x16& acc2, f32x16& acc3) {
;     ...
;     if (k0 + 128 < K) gt_load(t0, ap, bp, lda, ldb, KW(k0 + 128));
;     gt_compute(asr, bsr, acc0, acc1, acc2, acc3);
;     __syncthreads();
;     gt_store(t1, asw, bsw);
;     __syncthreads();
;     if (k0 + 192 < K) gt_load(t1, ap, bp, lda, ldb, KW(k0 + 192));
.Lmy_gw_4:
	s_cmp_lt_i32 s14, s28
	s_cselect_b32 s0, 0, -1
	s_cselect_b32 s1, 0, 0xfffffc00
	s_add_u32 s6, s12, s14
	s_addc_u32 s7, s13, s15
	s_add_u32 s6, s6, s1
	s_addc_u32 s7, s7, s0
	s_lshl_b64 s[6:7], s[6:7], 1
	v_lshl_add_u64 v[104:105], v[132:133], 0, s[6:7]
	v_add_co_u32_e32 v88, vcc, s4, v104
	v_lshl_add_u64 v[120:121], v[134:135], 0, s[6:7]
	s_nop 0
	v_addc_co_u32_e32 v89, vcc, 0, v105, vcc
	v_add_co_u32_e32 v92, vcc, 0x20000, v104
	s_nop 1
	v_addc_co_u32_e32 v93, vcc, 0, v105, vcc
	v_add_co_u32_e32 v112, vcc, 0x30000, v104
	global_load_dwordx4 v[88:91], v[88:89], off offset:384
	s_nop 0
	global_load_dwordx4 v[92:95], v[92:93], off offset:384
	v_addc_co_u32_e32 v113, vcc, 0, v105, vcc
	v_add_co_u32_e32 v116, vcc, 0x10000, v120
	global_load_dwordx4 v[104:107], v[104:105], off offset:384
	s_nop 0
	global_load_dwordx4 v[108:111], v[120:121], off offset:384
	v_addc_co_u32_e32 v117, vcc, 0, v121, vcc
	v_add_co_u32_e32 v122, vcc, 0x20000, v120
	global_load_dwordx4 v[112:115], v[112:113], off offset:384
	s_nop 0
	global_load_dwordx4 v[116:119], v[116:117], off offset:384
	v_addc_co_u32_e32 v123, vcc, 0, v121, vcc
	v_add_co_u32_e32 v124, vcc, 0x30000, v120
	s_nop 1
	v_addc_co_u32_e32 v125, vcc, 0, v121, vcc
	global_load_dwordx4 v[120:123], v[122:123], off offset:384
	s_nop 0
	global_load_dwordx4 v[124:127], v[124:125], off offset:384
	s_branch .LBB0_1318

; #define MFMA(a, b, c) __builtin_amdgcn_mfma_f32_32x32x16_bf16((a), (b), (c), 0, 0, 0)
; DI void gt_compute(const bf16* asr, const bf16* bsr, f32x16& acc0, f32x16& acc1, f32x16& acc2, f32x16& acc3) {
;   bf16x8 a[4], b0[4], b1[4], b2[4], b3[4];
; #pragma unroll
;   for (int kk = 0; kk < 4; ++kk) {
;     a[kk] = *(const bf16x8*)(asr + kk * 16);
;     b0[kk] = *(const bf16x8*)(bsr + kk * 16);
;     b1[kk] = *(const bf16x8*)(bsr + 32 * LDT + kk * 16);
;     b2[kk] = *(const bf16x8*)(bsr + 64 * LDT + kk * 16);
;     b3[kk] = *(const bf16x8*)(bsr + 96 * LDT + kk * 16);
;   }
;   __builtin_amdgcn_sched_barrier(0);
;   __builtin_amdgcn_s_setprio(2);
; #pragma unroll
;   for (int kk = 0; kk < 4; ++kk) {
;     acc0 = MFMA(a[kk], b0[kk], acc0); acc1 = MFMA(a[kk], b1[kk], acc1); acc2 = MFMA(a[kk], b2[kk], acc2); acc3 = MFMA(a[kk], b3[kk], acc3);
;   }
;   __builtin_amdgcn_s_setprio(0);
;   __builtin_amdgcn_sched_barrier(0);
; }
; DI void gemm_mainloop(const bf16* __restrict__ A, int lda, const bf16* __restrict__ Bt, int ldb, int K, int m0, int n0,
;                       bf16* As, bf16* Bs, f32x16& acc0, f32x16& acc1, f32x16& acc2, f32x16& acc3) {
;     ...
;   for (int k0 = 0; k0 < K; k0 += 128) {
;     __syncthreads();
;     gt_store(t0, asw, bsw);
;     __syncthreads();
;     if (k0 + 128 < K) gt_load(t0, ap, bp, lda, ldb, KW(k0 + 128));
;     gt_compute(asr, bsr, acc0, acc1, acc2, acc3);
;     __syncthreads();
;     gt_store(t1, asw, bsw);
;     __syncthreads();
;     if (k0 + 192 < K) gt_load(t1, ap, bp, lda, ldb, KW(k0 + 192));
;     gt_compute(asr, bsr, acc0, acc1, acc2, acc3);
.LBB0_1437:
	s_add_u32 s42, s40, 0x80
	s_addc_u32 s43, s41, 0
	s_cmpk_gt_u32 s40, 0x37f
	s_waitcnt vmcnt(63) expcnt(7) lgkmcnt(15)
	s_barrier
	s_waitcnt vmcnt(13)
	ds_write_b128 v134, v[72:75]
	ds_write_b128 v134, v[64:67] offset:4608
	ds_write_b128 v134, v[68:71] offset:9216
	s_waitcnt vmcnt(11)
	ds_write_b128 v134, v[80:83] offset:13824
	ds_write_b128 v134, v[76:79] offset:18432
	s_waitcnt vmcnt(10)
	ds_write_b128 v134, v[84:87] offset:23040
	s_waitcnt vmcnt(9)
	ds_write_b128 v134, v[96:99] offset:27648
	s_waitcnt vmcnt(8)
	ds_write_b128 v134, v[104:107] offset:32256
	s_waitcnt lgkmcnt(0)
	s_barrier
	s_cbranch_scc1 .LBB0_1439
	s_cmp_lt_i32 s42, s86
	s_cselect_b32 s1, 0, -1
	s_cselect_b32 s0, 0, 0xfffffc00
	s_add_u32 s2, s28, s40
	s_addc_u32 s3, s29, s41
	s_add_u32 s0, s2, s0
	s_addc_u32 s1, s3, s1
	s_lshl_b64 s[0:1], s[0:1], 1
	v_lshl_add_u64 v[72:73], v[130:131], 0, s[0:1]
	v_add_co_u32_e32 v64, vcc, s46, v72
	v_lshl_add_u64 v[96:97], v[132:133], 0, s[0:1]
	s_nop 0
	v_addc_co_u32_e32 v65, vcc, 0, v73, vcc
	v_add_co_u32_e32 v68, vcc, 0x20000, v72
	s_nop 1
	v_addc_co_u32_e32 v69, vcc, 0, v73, vcc
	v_add_co_u32_e32 v80, vcc, 0x30000, v72
	global_load_dwordx4 v[64:67], v[64:65], off offset:256
	s_nop 0
	global_load_dwordx4 v[68:71], v[68:69], off offset:256
	v_addc_co_u32_e32 v81, vcc, 0, v73, vcc
	v_add_co_u32_e32 v84, vcc, 0x10000, v96
	global_load_dwordx4 v[72:75], v[72:73], off offset:256
	s_nop 0
	global_load_dwordx4 v[76:79], v[96:97], off offset:256
	v_addc_co_u32_e32 v85, vcc, 0, v97, vcc
	v_add_co_u32_e32 v98, vcc, 0x20000, v96
	global_load_dwordx4 v[80:83], v[80:81], off offset:256
	s_nop 0
	global_load_dwordx4 v[84:87], v[84:85], off offset:256
	v_addc_co_u32_e32 v99, vcc, 0, v97, vcc
	v_add_co_u32_e32 v104, vcc, 0x30000, v96
	s_nop 1
	v_addc_co_u32_e32 v105, vcc, 0, v97, vcc
	global_load_dwordx4 v[96:99], v[98:99], off offset:256
	s_nop 0
	global_load_dwordx4 v[104:107], v[104:105], off offset:256
	ds_read_b128 v[148:151], v136
	ds_read_b128 v[152:155], v136 offset:32
	ds_read_b128 v[156:159], v128 offset:18432
	ds_read_b128 v[162:165], v128 offset:18464
	ds_read_b128 v[166:169], v128 offset:23040
	ds_read_b128 v[170:173], v128 offset:23072
	ds_read_b128 v[174:177], v128 offset:27648
	ds_read_b128 v[178:181], v128 offset:27680
	ds_read_b128 v[182:185], v128 offset:32256
	ds_read_b128 v[186:189], v128 offset:32288
	ds_read_b128 v[190:193], v136 offset:64
	ds_read_b128 v[194:197], v136 offset:96
	ds_read_b128 v[198:201], v128 offset:18496
	ds_read_b128 v[202:205], v128 offset:18528
	ds_read_b128 v[206:209], v128 offset:23104
	ds_read_b128 v[210:213], v128 offset:23136
	ds_read_b128 v[214:217], v128 offset:27712
	ds_read_b128 v[226:229], v128 offset:27744
	ds_read_b128 v[230:233], v128 offset:32320
	ds_read_b128 v[234:237], v128 offset:32352
	s_setprio 2
	s_waitcnt lgkmcnt(14)
	v_mfma_f32_32x32x16_bf16 v[32:47], v[148:151], v[156:159], v[32:47]
	v_mfma_f32_32x32x16_bf16 v[48:63], v[148:151], v[166:169], v[48:63]
	s_waitcnt lgkmcnt(13)
	v_mfma_f32_32x32x16_bf16 v[16:31], v[148:151], v[174:177], v[16:31]
	s_waitcnt lgkmcnt(11)
	v_mfma_f32_32x32x16_bf16 v[0:15], v[148:151], v[182:185], v[0:15]
	v_mfma_f32_32x32x16_bf16 v[32:47], v[152:155], v[162:165], v[32:47]
	v_mfma_f32_32x32x16_bf16 v[48:63], v[152:155], v[170:173], v[48:63]
	v_mfma_f32_32x32x16_bf16 v[16:31], v[152:155], v[178:181], v[16:31]
	s_waitcnt lgkmcnt(10)
	v_mfma_f32_32x32x16_bf16 v[0:15], v[152:155], v[186:189], v[0:15]
	s_waitcnt lgkmcnt(7)
	v_mfma_f32_32x32x16_bf16 v[32:47], v[190:193], v[198:201], v[32:47]
	s_waitcnt lgkmcnt(5)
	v_mfma_f32_32x32x16_bf16 v[48:63], v[190:193], v[206:209], v[48:63]
	s_waitcnt lgkmcnt(3)
	v_mfma_f32_32x32x16_bf16 v[16:31], v[190:193], v[214:217], v[16:31]
	s_waitcnt lgkmcnt(1)
	v_mfma_f32_32x32x16_bf16 v[0:15], v[190:193], v[230:233], v[0:15]
	v_mfma_f32_32x32x16_bf16 v[32:47], v[194:197], v[202:205], v[32:47]
	v_mfma_f32_32x32x16_bf16 v[48:63], v[194:197], v[210:213], v[48:63]
	v_mfma_f32_32x32x16_bf16 v[16:31], v[194:197], v[226:229], v[16:31]
	s_waitcnt lgkmcnt(0)
	v_mfma_f32_32x32x16_bf16 v[0:15], v[194:197], v[234:237], v[0:15]
	s_setprio 0
	s_cmpk_gt_u32 s40, 0x33f
	s_barrier
	s_waitcnt vmcnt(13)
	ds_write_b128 v134, v[100:103]
	ds_write_b128 v134, v[88:91] offset:4608
	ds_write_b128 v134, v[92:95] offset:9216
	s_waitcnt vmcnt(11)
	ds_write_b128 v134, v[112:115] offset:13824
	ds_write_b128 v134, v[108:111] offset:18432
	s_waitcnt vmcnt(10)
	ds_write_b128 v134, v[116:119] offset:23040
	s_waitcnt vmcnt(9)
	ds_write_b128 v134, v[120:123] offset:27648
	s_waitcnt vmcnt(8)
	ds_write_b128 v134, v[124:127] offset:32256
	s_waitcnt lgkmcnt(0)
	s_barrier
	s_cbranch_scc1 .LBB0_1436
	s_branch .Lmy_gw_5

; DI void gemm_mainloop(const bf16* __restrict__ A, int lda, const bf16* __restrict__ Bt, int ldb, int K, int m0, int n0,
;                       bf16* As, bf16* Bs, f32x16& acc0, f32x16& acc1, f32x16& acc2, f32x16& acc3) {
;     ...
;     if (k0 + 128 < K) gt_load(t0, ap, bp, lda, ldb, KW(k0 + 128));
;     gt_compute(asr, bsr, acc0, acc1, acc2, acc3);
;     __syncthreads();
;     gt_store(t1, asw, bsw);
;     __syncthreads();
;     if (k0 + 192 < K) gt_load(t1, ap, bp, lda, ldb, KW(k0 + 192));
.Lmy_gw_5:
	s_cmp_lt_i32 s40, s87
	s_cselect_b32 s1, 0, -1
	s_cselect_b32 s0, 0, 0xfffffc00
	s_add_u32 s2, s28, s40
	s_addc_u32 s3, s29, s41
	s_add_u32 s0, s2, s0
	s_addc_u32 s1, s3, s1
	s_lshl_b64 s[0:1], s[0:1], 1
	v_lshl_add_u64 v[100:101], v[130:131], 0, s[0:1]
	v_add_co_u32_e32 v88, vcc, s46, v100
	v_lshl_add_u64 v[120:121], v[132:133], 0, s[0:1]
	s_nop 0
	v_addc_co_u32_e32 v89, vcc, 0, v101, vcc
	v_add_co_u32_e32 v92, vcc, 0x20000, v100
	s_nop 1
	v_addc_co_u32_e32 v93, vcc, 0, v101, vcc
	v_add_co_u32_e32 v112, vcc, 0x30000, v100
	global_load_dwordx4 v[88:91], v[88:89], off offset:384
	s_nop 0
	global_load_dwordx4 v[92:95], v[92:93], off offset:384
	v_addc_co_u32_e32 v113, vcc, 0, v101, vcc
	v_add_co_u32_e32 v116, vcc, 0x10000, v120
	global_load_dwordx4 v[100:103], v[100:101], off offset:384
	s_nop 0
	global_load_dwordx4 v[108:111], v[120:121], off offset:384
	v_addc_co_u32_e32 v117, vcc, 0, v121, vcc
	v_add_co_u32_e32 v122, vcc, 0x20000, v120
	global_load_dwordx4 v[112:115], v[112:113], off offset:384
	s_nop 0
	global_load_dwordx4 v[116:119], v[116:117], off offset:384
	v_addc_co_u32_e32 v123, vcc, 0, v121, vcc
	v_add_co_u32_e32 v124, vcc, 0x30000, v120
	s_nop 1
	v_addc_co_u32_e32 v125, vcc, 0, v121, vcc
	global_load_dwordx4 v[120:123], v[122:123], off offset:384
	s_nop 0
	global_load_dwordx4 v[124:127], v[124:125], off offset:384
	s_branch .LBB0_1436
